# grid barriers 2..16: agent-scope L1 invalidate issued when the workgroup arrives (after its last pre-barrier load) instead of after release, so it overlaps the wait
# speedup vs baseline: 1.0274x; 1.0161x over previous
.LBB0_141:
	s_waitcnt vmcnt(0)
	v_mov_b32_e32 v0, v205
	s_barrier
	s_nop 0
	v_cmp_eq_u32_e32 vcc, 0, v0
	s_and_saveexec_b64 s[0:1], vcc
	s_cbranch_execz .LBB0_193
	buffer_inv sc1
	v_mov_b32_e32 v0, 0x12000
	ds_read_b64 v[2:3], v0
	s_getreg_b32 s98, hwreg(HW_REG_XCC_ID, 0, 4)
	s_and_b32 s98, s98, 15
	s_lshl_b32 s98, s98, 8
	v_mov_b32_e32 v1, 1
	s_add_u32 s100, s98, 0x1dc01400
	s_add_u32 s101, s98, 0x1dc02400
	v_mov_b32_e32 v4, s100
	s_waitcnt vmcnt(0) expcnt(0) lgkmcnt(0)
	global_atomic_add v5, v4, v1, s[26:27] sc0
	v_mul_lo_u32 v6, v2, 2
	s_waitcnt vmcnt(0)
	v_add_u32_e32 v5, 1, v5
	v_cmp_eq_u32_e32 vcc, v5, v6
	s_cbranch_vccz .Lxb1_spin
	buffer_wbl2 sc1
	s_waitcnt vmcnt(0)
	v_mov_b32_e32 v4, 0x1dc03400
	global_atomic_add v5, v4, v1, s[26:27] sc0
	v_mul_lo_u32 v6, v3, 2
	s_waitcnt vmcnt(0)
	v_add_u32_e32 v5, 1, v5
	v_cmp_eq_u32_e32 vcc, v5, v6
	s_cbranch_vccz .Lxb1_spin
	v_mov_b32_e32 v4, 0x1dc02400
	global_atomic_add v4, v1, s[26:27]
	global_atomic_add v4, v1, s[26:27] offset:256
	global_atomic_add v4, v1, s[26:27] offset:512
	global_atomic_add v4, v1, s[26:27] offset:768
	global_atomic_add v4, v1, s[26:27] offset:1024
	global_atomic_add v4, v1, s[26:27] offset:1280
	global_atomic_add v4, v1, s[26:27] offset:1536
	global_atomic_add v4, v1, s[26:27] offset:1792
	global_atomic_add v4, v1, s[26:27] offset:2048
	global_atomic_add v4, v1, s[26:27] offset:2304
	global_atomic_add v4, v1, s[26:27] offset:2560
	global_atomic_add v4, v1, s[26:27] offset:2816
	global_atomic_add v4, v1, s[26:27] offset:3072
	global_atomic_add v4, v1, s[26:27] offset:3328
	global_atomic_add v4, v1, s[26:27] offset:3584
	global_atomic_add v4, v1, s[26:27] offset:3840
	s_waitcnt vmcnt(0)
	s_branch .Lxb1_done

.Lxb1_loop:
	global_load_dword v5, v4, s[26:27] sc1
	s_waitcnt vmcnt(0)
	v_cmp_ne_u32_e32 vcc, 1, v5
	s_cbranch_vccnz .Lxb1_done
	s_sleep 1
	s_add_u32 s99, s99, 1
	s_cmp_lt_u32 s99, 0x8000
	s_cbranch_scc1 .Lxb1_loop
.Lxb1_done:
	s_waitcnt vmcnt(0)
.LBB0_193:
	s_or_b64 exec, exec, s[0:1]
	s_cmpk_lt_i32 s2, 0x800
	s_cselect_b64 s[8:9], -1, 0
	s_cmpk_gt_i32 s2, 0x7ff
	s_waitcnt lgkmcnt(0)
	s_barrier
	s_cbranch_scc1 .LBB0_200
	s_add_u32 s3, s26, 0x15800000
	s_addc_u32 s16, s27, 0
	s_add_u32 s17, s26, 0x1da00000
	s_addc_u32 s18, s27, 0
	s_add_u32 s19, s26, 0x1d800000
	s_addc_u32 s20, s27, 0
	s_lshl_b32 s21, s2, 4
	s_lshl_b32 s64, s92, 4
	s_movk_i32 s65, 0x7f
	s_waitcnt vmcnt(7)
	v_mov_b32_e32 v65, 0
	s_movk_i32 s68, 0x1000
	s_mov_b32 s11, 0
	s_movk_i32 s69, 0x2000
	s_movk_i32 s70, 0x3000
	s_movk_i32 s71, 0x4000
	s_movk_i32 s72, 0x5000
	s_movk_i32 s73, 0x6000
	s_movk_i32 s74, 0x7000
	s_mov_b32 s75, 0xbfb8aa3b
	s_mov_b32 s76, 0x800000
	s_mov_b32 s77, 0x3f317217
	s_mov_b32 s78, 0x7f800000
	s_waitcnt vmcnt(6)
	v_mov_b32_e32 v72, 0x41b17218
	s_mov_b32 s79, 0x3d800000
	s_movk_i32 s80, 0x1800
	s_movk_i32 s81, 0x90
	s_movk_i32 s82, 0x80
	s_mov_b32 s83, 0x5040100
	s_mov_b32 s12, s2
	s_branch .LBB0_196

.LBB0_200:
	s_waitcnt vmcnt(0)
	v_mov_b32_e32 v0, v205
	s_barrier
	s_nop 0
	v_cmp_eq_u32_e32 vcc, 0, v0
	s_and_saveexec_b64 s[0:1], vcc
	s_cbranch_execz .LBB0_252
	buffer_inv sc1
	v_mov_b32_e32 v0, 0x12000
	ds_read_b64 v[2:3], v0
	s_getreg_b32 s98, hwreg(HW_REG_XCC_ID, 0, 4)
	s_and_b32 s98, s98, 15
	s_lshl_b32 s98, s98, 8
	v_mov_b32_e32 v1, 1
	s_add_u32 s100, s98, 0x1dc01400
	s_add_u32 s101, s98, 0x1dc02400
	v_mov_b32_e32 v4, s100
	s_waitcnt vmcnt(0) expcnt(0) lgkmcnt(0)
	global_atomic_add v5, v4, v1, s[26:27] sc0
	v_mul_lo_u32 v6, v2, 3
	s_waitcnt vmcnt(0)
	v_add_u32_e32 v5, 1, v5
	v_cmp_eq_u32_e32 vcc, v5, v6
	s_cbranch_vccz .Lxb2_spin
	buffer_wbl2 sc1
	s_waitcnt vmcnt(0)
	v_mov_b32_e32 v4, 0x1dc03400
	global_atomic_add v5, v4, v1, s[26:27] sc0
	v_mul_lo_u32 v6, v3, 3
	s_waitcnt vmcnt(0)
	v_add_u32_e32 v5, 1, v5
	v_cmp_eq_u32_e32 vcc, v5, v6
	s_cbranch_vccz .Lxb2_spin
	v_mov_b32_e32 v4, 0x1dc02400
	global_atomic_add v4, v1, s[26:27]
	global_atomic_add v4, v1, s[26:27] offset:256
	global_atomic_add v4, v1, s[26:27] offset:512
	global_atomic_add v4, v1, s[26:27] offset:768
	global_atomic_add v4, v1, s[26:27] offset:1024
	global_atomic_add v4, v1, s[26:27] offset:1280
	global_atomic_add v4, v1, s[26:27] offset:1536
	global_atomic_add v4, v1, s[26:27] offset:1792
	global_atomic_add v4, v1, s[26:27] offset:2048
	global_atomic_add v4, v1, s[26:27] offset:2304
	global_atomic_add v4, v1, s[26:27] offset:2560
	global_atomic_add v4, v1, s[26:27] offset:2816
	global_atomic_add v4, v1, s[26:27] offset:3072
	global_atomic_add v4, v1, s[26:27] offset:3328
	global_atomic_add v4, v1, s[26:27] offset:3584
	global_atomic_add v4, v1, s[26:27] offset:3840
	s_waitcnt vmcnt(0)
	s_branch .Lxb2_done

.Lxb2_loop:
	global_load_dword v5, v4, s[26:27] sc1
	s_waitcnt vmcnt(0)
	v_cmp_ne_u32_e32 vcc, 2, v5
	s_cbranch_vccnz .Lxb2_done
	s_sleep 1
	s_add_u32 s99, s99, 1
	s_cmp_lt_u32 s99, 0x8000
	s_cbranch_scc1 .Lxb2_loop
.Lxb2_done:
	s_waitcnt vmcnt(0)
.LBB0_252:
	s_or_b64 exec, exec, s[0:1]
	s_waitcnt lgkmcnt(0)
	v_mov_b32_e32 v0, v205
	s_barrier
	s_mov_b32 s0, 0x20000
	v_lshl_add_u32 v6, s2, 8, v0
	v_cmp_gt_i32_e32 vcc, s0, v6
	s_and_saveexec_b64 s[10:11], vcc
	s_cbranch_execz .LBB0_257
	v_lshlrev_b32_e32 v0, 1, v0
	s_lshl_b32 s3, s92, 8
	v_lshl_add_u32 v7, s2, 9, v0
	s_lshl_b32 s18, s92, 9
	s_mov_b64 s[12:13], 0
	s_mov_b32 s19, 0x1da01000
	s_mov_b32 s20, 0x1da02000
	s_mov_b32 s21, 0x1da03000
	s_mov_b64 s[14:15], 0x200000
	s_mov_b64 s[16:17], 0x4000
	s_mov_b32 s46, 0x1ffff

.LBB0_257:
	s_or_b64 exec, exec, s[10:11]
	s_waitcnt vmcnt(0)
	v_mov_b32_e32 v0, v205
	s_barrier
	s_nop 0
	v_cmp_eq_u32_e32 vcc, 0, v0
	s_and_saveexec_b64 s[0:1], vcc
	s_cbranch_execz .LBB0_309
	buffer_inv sc1
	v_mov_b32_e32 v0, 0x12000
	ds_read_b64 v[2:3], v0
	s_getreg_b32 s98, hwreg(HW_REG_XCC_ID, 0, 4)
	s_and_b32 s98, s98, 15
	s_lshl_b32 s98, s98, 8
	v_mov_b32_e32 v1, 1
	s_add_u32 s100, s98, 0x1dc01400
	s_add_u32 s101, s98, 0x1dc02400
	v_mov_b32_e32 v4, s100
	s_waitcnt vmcnt(0) expcnt(0) lgkmcnt(0)
	global_atomic_add v5, v4, v1, s[26:27] sc0
	v_mul_lo_u32 v6, v2, 4
	s_waitcnt vmcnt(0)
	v_add_u32_e32 v5, 1, v5
	v_cmp_eq_u32_e32 vcc, v5, v6
	s_cbranch_vccz .Lxb3_spin
	buffer_wbl2 sc1
	s_waitcnt vmcnt(0)
	v_mov_b32_e32 v4, 0x1dc03400
	global_atomic_add v5, v4, v1, s[26:27] sc0
	v_mul_lo_u32 v6, v3, 4
	s_waitcnt vmcnt(0)
	v_add_u32_e32 v5, 1, v5
	v_cmp_eq_u32_e32 vcc, v5, v6
	s_cbranch_vccz .Lxb3_spin
	v_mov_b32_e32 v4, 0x1dc02400
	global_atomic_add v4, v1, s[26:27]
	global_atomic_add v4, v1, s[26:27] offset:256
	global_atomic_add v4, v1, s[26:27] offset:512
	global_atomic_add v4, v1, s[26:27] offset:768
	global_atomic_add v4, v1, s[26:27] offset:1024
	global_atomic_add v4, v1, s[26:27] offset:1280
	global_atomic_add v4, v1, s[26:27] offset:1536
	global_atomic_add v4, v1, s[26:27] offset:1792
	global_atomic_add v4, v1, s[26:27] offset:2048
	global_atomic_add v4, v1, s[26:27] offset:2304
	global_atomic_add v4, v1, s[26:27] offset:2560
	global_atomic_add v4, v1, s[26:27] offset:2816
	global_atomic_add v4, v1, s[26:27] offset:3072
	global_atomic_add v4, v1, s[26:27] offset:3328
	global_atomic_add v4, v1, s[26:27] offset:3584
	global_atomic_add v4, v1, s[26:27] offset:3840
	s_waitcnt vmcnt(0)
	s_branch .Lxb3_done

.Lxb3_loop:
	global_load_dword v5, v4, s[26:27] sc1
	s_waitcnt vmcnt(0)
	v_cmp_ne_u32_e32 vcc, 3, v5
	s_cbranch_vccnz .Lxb3_done
	s_sleep 1
	s_add_u32 s99, s99, 1
	s_cmp_lt_u32 s99, 0x8000
	s_cbranch_scc1 .Lxb3_loop
.Lxb3_done:
	s_waitcnt vmcnt(0)
.LBB0_309:
	s_or_b64 exec, exec, s[0:1]
	s_add_u32 s46, s26, 0x15800000
	s_addc_u32 s47, s27, 0
	s_andn2_b64 vcc, exec, s[8:9]
	s_waitcnt lgkmcnt(0)
	s_barrier
	s_cbranch_vccnz .LBB0_314
	v_cndmask_b32_e64 v0, 0, 1, s[6:7]
	v_mbcnt_hi_u32_b32 v174, -1, v207
	v_readfirstlane_b32 s19, v0
	v_and_b32_e32 v0, 64, v174
	s_lshl_b32 s3, s2, 4
	s_lshl_b32 s18, s92, 4
	s_add_i32 s19, s19, s96
	s_movk_i32 s20, 0xffc0
	s_movk_i32 s21, 0xffe0
	s_movk_i32 s48, 0x2200
	s_movk_i32 s49, 0x1800
	s_mov_b32 s7, 0
	s_mov_b32 s64, 0x9801000
	s_mov_b32 s65, 0x5801000
	s_mov_b32 s68, 0x9803000
	s_mov_b32 s69, 0x9804000
	s_mov_b32 s70, 0x5802000
	s_mov_b32 s71, 0x9806000
	s_mov_b32 s72, 0x9807000
	s_mov_b32 s73, 0x5803000
	s_mov_b32 s74, 0x9809000
	s_mov_b32 s75, 0x980a000
	s_mov_b64 s[8:9], 0xc000
	s_mov_b64 s[10:11], 0x4000
	s_movk_i32 s76, 0x110
	s_movk_i32 s77, 0x90
	v_mov_b64_e32 v[164:165], s[44:45]
	v_mov_b32_e32 v167, 0
	s_mov_b32 s78, 0x5040100
	s_mov_b64 s[12:13], 0x8000
	s_mov_b32 s79, 0x8000
	s_movk_i32 s80, 0x840
	s_movk_i32 s81, 0x210
	v_xor_b32_e32 v175, 1, v174
	v_add_u32_e32 v176, 64, v0
	v_xor_b32_e32 v177, 2, v174
	s_mov_b64 s[14:15], 0x1000
	s_movk_i32 s82, 0x1000
	v_mov_b32_e32 v178, 0x358637bd
	s_mov_b32 s83, 0x800000
	s_mov_b32 s84, s2
	s_mov_b32 s16, s2

.LBB0_314:
	s_waitcnt vmcnt(0)
	v_mov_b32_e32 v0, v205
	s_barrier
	s_nop 0
	v_cmp_eq_u32_e32 vcc, 0, v0
	s_and_saveexec_b64 s[0:1], vcc
	s_cbranch_execz .LBB0_366
	buffer_inv sc1
	v_mov_b32_e32 v0, 0x12000
	ds_read_b64 v[2:3], v0
	s_getreg_b32 s98, hwreg(HW_REG_XCC_ID, 0, 4)
	s_and_b32 s98, s98, 15
	s_lshl_b32 s98, s98, 8
	v_mov_b32_e32 v1, 1
	s_add_u32 s100, s98, 0x1dc01400
	s_add_u32 s101, s98, 0x1dc02400
	v_mov_b32_e32 v4, s100
	s_waitcnt vmcnt(0) expcnt(0) lgkmcnt(0)
	global_atomic_add v5, v4, v1, s[26:27] sc0
	v_mul_lo_u32 v6, v2, 5
	s_waitcnt vmcnt(0)
	v_add_u32_e32 v5, 1, v5
	v_cmp_eq_u32_e32 vcc, v5, v6
	s_cbranch_vccz .Lxb4_spin
	buffer_wbl2 sc1
	s_waitcnt vmcnt(0)
	v_mov_b32_e32 v4, 0x1dc03400
	global_atomic_add v5, v4, v1, s[26:27] sc0
	v_mul_lo_u32 v6, v3, 5
	s_waitcnt vmcnt(0)
	v_add_u32_e32 v5, 1, v5
	v_cmp_eq_u32_e32 vcc, v5, v6
	s_cbranch_vccz .Lxb4_spin
	v_mov_b32_e32 v4, 0x1dc02400
	global_atomic_add v4, v1, s[26:27]
	global_atomic_add v4, v1, s[26:27] offset:256
	global_atomic_add v4, v1, s[26:27] offset:512
	global_atomic_add v4, v1, s[26:27] offset:768
	global_atomic_add v4, v1, s[26:27] offset:1024
	global_atomic_add v4, v1, s[26:27] offset:1280
	global_atomic_add v4, v1, s[26:27] offset:1536
	global_atomic_add v4, v1, s[26:27] offset:1792
	global_atomic_add v4, v1, s[26:27] offset:2048
	global_atomic_add v4, v1, s[26:27] offset:2304
	global_atomic_add v4, v1, s[26:27] offset:2560
	global_atomic_add v4, v1, s[26:27] offset:2816
	global_atomic_add v4, v1, s[26:27] offset:3072
	global_atomic_add v4, v1, s[26:27] offset:3328
	global_atomic_add v4, v1, s[26:27] offset:3584
	global_atomic_add v4, v1, s[26:27] offset:3840
	s_waitcnt vmcnt(0)
	s_branch .Lxb4_done

.Lxb4_loop:
	global_load_dword v5, v4, s[26:27] sc1
	s_waitcnt vmcnt(0)
	v_cmp_ne_u32_e32 vcc, 4, v5
	s_cbranch_vccnz .Lxb4_done
	s_sleep 1
	s_add_u32 s99, s99, 1
	s_cmp_lt_u32 s99, 0x8000
	s_cbranch_scc1 .Lxb4_loop
.Lxb4_done:
	s_waitcnt vmcnt(0)
.LBB0_366:
	s_or_b64 exec, exec, s[0:1]
	s_waitcnt lgkmcnt(0)
	v_cndmask_b32_e64 v0, 0, 1, s[4:5]
	v_cmp_ne_u32_e64 s[0:1], 1, v0
	s_andn2_b64 vcc, exec, s[4:5]
	s_mov_b32 s3, s2
	s_barrier
	s_cbranch_vccz .LBB0_368
	s_cmpk_gt_i32 s3, 0x7ff
	s_cbranch_scc0 .LBB0_369
	s_branch .LBB0_381

.LBB0_381:
	s_waitcnt vmcnt(0)
	v_mov_b32_e32 v0, v205
	s_barrier
	s_nop 0
	v_cmp_eq_u32_e32 vcc, 0, v0
	s_and_saveexec_b64 s[4:5], vcc
	s_cbranch_execz .LBB0_433
	buffer_inv sc1
	v_mov_b32_e32 v0, 0x12000
	ds_read_b64 v[2:3], v0
	s_getreg_b32 s98, hwreg(HW_REG_XCC_ID, 0, 4)
	s_and_b32 s98, s98, 15
	s_lshl_b32 s98, s98, 8
	v_mov_b32_e32 v1, 1
	s_add_u32 s100, s98, 0x1dc01400
	s_add_u32 s101, s98, 0x1dc02400
	v_mov_b32_e32 v4, s100
	s_waitcnt vmcnt(0) expcnt(0) lgkmcnt(0)
	global_atomic_add v5, v4, v1, s[26:27] sc0
	v_mul_lo_u32 v6, v2, 6
	s_waitcnt vmcnt(0)
	v_add_u32_e32 v5, 1, v5
	v_cmp_eq_u32_e32 vcc, v5, v6
	s_cbranch_vccz .Lxb5_spin
	buffer_wbl2 sc1
	s_waitcnt vmcnt(0)
	v_mov_b32_e32 v4, 0x1dc03400
	global_atomic_add v5, v4, v1, s[26:27] sc0
	v_mul_lo_u32 v6, v3, 6
	s_waitcnt vmcnt(0)
	v_add_u32_e32 v5, 1, v5
	v_cmp_eq_u32_e32 vcc, v5, v6
	s_cbranch_vccz .Lxb5_spin
	v_mov_b32_e32 v4, 0x1dc02400
	global_atomic_add v4, v1, s[26:27]
	global_atomic_add v4, v1, s[26:27] offset:256
	global_atomic_add v4, v1, s[26:27] offset:512
	global_atomic_add v4, v1, s[26:27] offset:768
	global_atomic_add v4, v1, s[26:27] offset:1024
	global_atomic_add v4, v1, s[26:27] offset:1280
	global_atomic_add v4, v1, s[26:27] offset:1536
	global_atomic_add v4, v1, s[26:27] offset:1792
	global_atomic_add v4, v1, s[26:27] offset:2048
	global_atomic_add v4, v1, s[26:27] offset:2304
	global_atomic_add v4, v1, s[26:27] offset:2560
	global_atomic_add v4, v1, s[26:27] offset:2816
	global_atomic_add v4, v1, s[26:27] offset:3072
	global_atomic_add v4, v1, s[26:27] offset:3328
	global_atomic_add v4, v1, s[26:27] offset:3584
	global_atomic_add v4, v1, s[26:27] offset:3840
	s_waitcnt vmcnt(0)
	s_branch .Lxb5_done

.Lxb5_loop:
	global_load_dword v5, v4, s[26:27] sc1
	s_waitcnt vmcnt(0)
	v_cmp_ne_u32_e32 vcc, 5, v5
	s_cbranch_vccnz .Lxb5_done
	s_sleep 1
	s_add_u32 s99, s99, 1
	s_cmp_lt_u32 s99, 0x8000
	s_cbranch_scc1 .Lxb5_loop
.Lxb5_done:
	s_waitcnt vmcnt(0)
.LBB0_433:
	s_or_b64 exec, exec, s[4:5]
	s_waitcnt lgkmcnt(0)
	v_mov_b32_e32 v0, v205
	v_mov_b32_e32 v1, v205
	s_barrier
	s_mov_b32 s3, 0x8000
	v_ashrrev_i32_e32 v1, 6, v1
	v_add_u32_e32 v16, s93, v1
	v_cmp_gt_i32_e32 vcc, s3, v16
	s_and_saveexec_b64 s[6:7], vcc
	s_cbranch_execz .LBB0_436
	v_and_b32_e32 v17, 63, v0
	v_lshlrev_b32_e32 v18, 4, v17
	global_load_dwordx4 v[0:3], v18, s[42:43]
	global_load_dwordx4 v[4:7], v18, s[42:43] offset:1024
	global_load_dwordx4 v[8:11], v18, s[42:43] offset:2048
	global_load_dwordx4 v[12:15], v18, s[42:43] offset:3072
	v_mbcnt_hi_u32_b32 v20, -1, v207
	v_and_b32_e32 v19, 64, v20
	v_add_u32_e32 v21, 64, v19
	v_xor_b32_e32 v22, 32, v20
	v_cmp_lt_i32_e32 vcc, v22, v21
	v_mov_b32_e32 v19, 0
	s_lshl_b32 s3, s92, 2
	v_cndmask_b32_e32 v22, v20, v22, vcc
	v_lshlrev_b32_e32 v28, 2, v22
	v_xor_b32_e32 v22, 16, v20
	v_cmp_lt_i32_e32 vcc, v22, v21
	s_mov_b64 s[8:9], 0
	v_mov_b32_e32 v23, v19
	v_cndmask_b32_e32 v22, v20, v22, vcc
	v_lshlrev_b32_e32 v29, 2, v22
	v_xor_b32_e32 v22, 8, v20
	v_cmp_lt_i32_e32 vcc, v22, v21
	v_mov_b32_e32 v25, v19
	v_mov_b32_e32 v34, 0x358637bd
	v_cndmask_b32_e32 v22, v20, v22, vcc
	v_lshlrev_b32_e32 v30, 2, v22
	v_xor_b32_e32 v22, 4, v20
	v_cmp_lt_i32_e32 vcc, v22, v21
	s_mov_b32 s10, 0x800000
	v_mov_b32_e32 v27, v19
	v_cndmask_b32_e32 v22, v20, v22, vcc
	v_lshlrev_b32_e32 v31, 2, v22
	v_xor_b32_e32 v22, 2, v20
	v_cmp_lt_i32_e32 vcc, v22, v21
	s_movk_i32 s11, 0x7fff
	s_nop 0
	v_cndmask_b32_e32 v22, v20, v22, vcc
	v_lshlrev_b32_e32 v32, 2, v22
	v_xor_b32_e32 v22, 1, v20
	v_cmp_lt_i32_e32 vcc, v22, v21
	s_nop 1
	v_cndmask_b32_e32 v20, v20, v22, vcc
	v_lshlrev_b32_e32 v22, 2, v17
	v_or_b32_e32 v24, 0x100, v22
	v_or_b32_e32 v26, 0x200, v22
	v_or_b32_e32 v36, 0x300, v22
	v_lshlrev_b32_e32 v33, 2, v20
	v_lshl_add_u64 v[20:21], s[24:25], 0, v[18:19]
	v_lshlrev_b32_e32 v18, 1, v22
	v_lshlrev_b32_e32 v22, 1, v24
	v_lshlrev_b32_e32 v24, 1, v26
	v_lshlrev_b32_e32 v26, 1, v36

.LBB0_436:
	s_or_b64 exec, exec, s[6:7]
	s_waitcnt vmcnt(0)
	v_mov_b32_e32 v0, v205
	s_barrier
	s_nop 0
	v_cmp_eq_u32_e32 vcc, 0, v0
	s_and_saveexec_b64 s[4:5], vcc
	s_cbranch_execz .LBB0_488
	buffer_inv sc1
	v_mov_b32_e32 v0, 0x12000
	ds_read_b64 v[2:3], v0
	s_getreg_b32 s98, hwreg(HW_REG_XCC_ID, 0, 4)
	s_and_b32 s98, s98, 15
	s_lshl_b32 s98, s98, 8
	v_mov_b32_e32 v1, 1
	s_add_u32 s100, s98, 0x1dc01400
	s_add_u32 s101, s98, 0x1dc02400
	v_mov_b32_e32 v4, s100
	s_waitcnt vmcnt(0) expcnt(0) lgkmcnt(0)
	global_atomic_add v5, v4, v1, s[26:27] sc0
	v_mul_lo_u32 v6, v2, 7
	s_waitcnt vmcnt(0)
	v_add_u32_e32 v5, 1, v5
	v_cmp_eq_u32_e32 vcc, v5, v6
	s_cbranch_vccz .Lxb6_spin
	buffer_wbl2 sc1
	s_waitcnt vmcnt(0)
	v_mov_b32_e32 v4, 0x1dc03400
	global_atomic_add v5, v4, v1, s[26:27] sc0
	v_mul_lo_u32 v6, v3, 7
	s_waitcnt vmcnt(0)
	v_add_u32_e32 v5, 1, v5
	v_cmp_eq_u32_e32 vcc, v5, v6
	s_cbranch_vccz .Lxb6_spin
	v_mov_b32_e32 v4, 0x1dc02400
	global_atomic_add v4, v1, s[26:27]
	global_atomic_add v4, v1, s[26:27] offset:256
	global_atomic_add v4, v1, s[26:27] offset:512
	global_atomic_add v4, v1, s[26:27] offset:768
	global_atomic_add v4, v1, s[26:27] offset:1024
	global_atomic_add v4, v1, s[26:27] offset:1280
	global_atomic_add v4, v1, s[26:27] offset:1536
	global_atomic_add v4, v1, s[26:27] offset:1792
	global_atomic_add v4, v1, s[26:27] offset:2048
	global_atomic_add v4, v1, s[26:27] offset:2304
	global_atomic_add v4, v1, s[26:27] offset:2560
	global_atomic_add v4, v1, s[26:27] offset:2816
	global_atomic_add v4, v1, s[26:27] offset:3072
	global_atomic_add v4, v1, s[26:27] offset:3328
	global_atomic_add v4, v1, s[26:27] offset:3584
	global_atomic_add v4, v1, s[26:27] offset:3840
	s_waitcnt vmcnt(0)
	s_branch .Lxb6_done

.Lxb6_loop:
	global_load_dword v5, v4, s[26:27] sc1
	s_waitcnt vmcnt(0)
	v_cmp_ne_u32_e32 vcc, 6, v5
	s_cbranch_vccnz .Lxb6_done
	s_sleep 1
	s_add_u32 s99, s99, 1
	s_cmp_lt_u32 s99, 0x8000
	s_cbranch_scc1 .Lxb6_loop
.Lxb6_done:
	s_waitcnt vmcnt(0)
.LBB0_488:
	s_or_b64 exec, exec, s[4:5]
	s_and_b64 vcc, exec, s[0:1]
	s_mov_b32 s64, s2
	s_waitcnt lgkmcnt(0)
	s_barrier
	s_cbranch_vccz .LBB0_490
	s_add_u32 s3, s26, 0x1200000
	s_addc_u32 s86, s27, 0
	s_cmpk_gt_i32 s64, 0x7ff
	s_cbranch_scc0 .LBB0_491
	s_branch .LBB0_503

.LBB0_503:
	s_waitcnt vmcnt(0)
	v_mov_b32_e32 v0, v205
	s_barrier
	s_nop 0
	v_cmp_eq_u32_e32 vcc, 0, v0
	s_and_saveexec_b64 s[4:5], vcc
	s_cbranch_execz .LBB0_555
	buffer_inv sc1
	v_mov_b32_e32 v0, 0x12000
	ds_read_b64 v[2:3], v0
	s_getreg_b32 s98, hwreg(HW_REG_XCC_ID, 0, 4)
	s_and_b32 s98, s98, 15
	s_lshl_b32 s98, s98, 8
	v_mov_b32_e32 v1, 1
	s_add_u32 s100, s98, 0x1dc01400
	s_add_u32 s101, s98, 0x1dc02400
	v_mov_b32_e32 v4, s100
	s_waitcnt vmcnt(0) expcnt(0) lgkmcnt(0)
	global_atomic_add v5, v4, v1, s[26:27] sc0
	v_mul_lo_u32 v6, v2, 8
	s_waitcnt vmcnt(0)
	v_add_u32_e32 v5, 1, v5
	v_cmp_eq_u32_e32 vcc, v5, v6
	s_cbranch_vccz .Lxb7_spin
	buffer_wbl2 sc1
	s_waitcnt vmcnt(0)
	v_mov_b32_e32 v4, 0x1dc03400
	global_atomic_add v5, v4, v1, s[26:27] sc0
	v_mul_lo_u32 v6, v3, 8
	s_waitcnt vmcnt(0)
	v_add_u32_e32 v5, 1, v5
	v_cmp_eq_u32_e32 vcc, v5, v6
	s_cbranch_vccz .Lxb7_spin
	v_mov_b32_e32 v4, 0x1dc02400
	global_atomic_add v4, v1, s[26:27]
	global_atomic_add v4, v1, s[26:27] offset:256
	global_atomic_add v4, v1, s[26:27] offset:512
	global_atomic_add v4, v1, s[26:27] offset:768
	global_atomic_add v4, v1, s[26:27] offset:1024
	global_atomic_add v4, v1, s[26:27] offset:1280
	global_atomic_add v4, v1, s[26:27] offset:1536
	global_atomic_add v4, v1, s[26:27] offset:1792
	global_atomic_add v4, v1, s[26:27] offset:2048
	global_atomic_add v4, v1, s[26:27] offset:2304
	global_atomic_add v4, v1, s[26:27] offset:2560
	global_atomic_add v4, v1, s[26:27] offset:2816
	global_atomic_add v4, v1, s[26:27] offset:3072
	global_atomic_add v4, v1, s[26:27] offset:3328
	global_atomic_add v4, v1, s[26:27] offset:3584
	global_atomic_add v4, v1, s[26:27] offset:3840
	s_waitcnt vmcnt(0)
	s_branch .Lxb7_done

.Lxb7_loop:
	global_load_dword v5, v4, s[26:27] sc1
	s_waitcnt vmcnt(0)
	v_cmp_ne_u32_e32 vcc, 7, v5
	s_cbranch_vccnz .Lxb7_done
	s_sleep 1
	s_add_u32 s99, s99, 1
	s_cmp_lt_u32 s99, 0x8000
	s_cbranch_scc1 .Lxb7_loop
.Lxb7_done:
	s_waitcnt vmcnt(0)
.LBB0_555:
	s_or_b64 exec, exec, s[4:5]
	s_add_u32 s20, s26, 0xd800000
	s_addc_u32 s21, s27, 0
	s_waitcnt lgkmcnt(0)
	v_mov_b32_e32 v0, v205
	s_add_u32 s48, s26, 0xe800000
	s_barrier
	s_addc_u32 s49, s27, 0
	v_ashrrev_i32_e32 v1, 6, v0
	s_add_u32 s36, s26, 0xf800000
	v_add_u32_e32 v176, s93, v1
	s_mov_b32 s4, 0x8000
	s_addc_u32 s37, s27, 0
	v_cmp_gt_i32_e32 vcc, s4, v176
	s_and_saveexec_b64 s[6:7], vcc
	s_cbranch_execz .LBB0_578

.LBB0_578:
	s_or_b64 exec, exec, s[6:7]
	s_waitcnt vmcnt(0)
	v_mov_b32_e32 v0, v205
	s_barrier
	s_nop 0
	v_cmp_eq_u32_e32 vcc, 0, v0
	s_and_saveexec_b64 s[4:5], vcc
	s_cbranch_execz .LBB0_630
	buffer_inv sc1
	v_mov_b32_e32 v0, 0x12000
	ds_read_b64 v[2:3], v0
	s_getreg_b32 s98, hwreg(HW_REG_XCC_ID, 0, 4)
	s_and_b32 s98, s98, 15
	s_lshl_b32 s98, s98, 8
	v_mov_b32_e32 v1, 1
	s_add_u32 s100, s98, 0x1dc01400
	s_add_u32 s101, s98, 0x1dc02400
	v_mov_b32_e32 v4, s100
	s_waitcnt vmcnt(0) expcnt(0) lgkmcnt(0)
	global_atomic_add v5, v4, v1, s[26:27] sc0
	v_mul_lo_u32 v6, v2, 9
	s_waitcnt vmcnt(0)
	v_add_u32_e32 v5, 1, v5
	v_cmp_eq_u32_e32 vcc, v5, v6
	s_cbranch_vccz .Lxb8_spin
	buffer_wbl2 sc1
	s_waitcnt vmcnt(0)
	v_mov_b32_e32 v4, 0x1dc03400
	global_atomic_add v5, v4, v1, s[26:27] sc0
	v_mul_lo_u32 v6, v3, 9
	s_waitcnt vmcnt(0)
	v_add_u32_e32 v5, 1, v5
	v_cmp_eq_u32_e32 vcc, v5, v6
	s_cbranch_vccz .Lxb8_spin
	v_mov_b32_e32 v4, 0x1dc02400
	global_atomic_add v4, v1, s[26:27]
	global_atomic_add v4, v1, s[26:27] offset:256
	global_atomic_add v4, v1, s[26:27] offset:512
	global_atomic_add v4, v1, s[26:27] offset:768
	global_atomic_add v4, v1, s[26:27] offset:1024
	global_atomic_add v4, v1, s[26:27] offset:1280
	global_atomic_add v4, v1, s[26:27] offset:1536
	global_atomic_add v4, v1, s[26:27] offset:1792
	global_atomic_add v4, v1, s[26:27] offset:2048
	global_atomic_add v4, v1, s[26:27] offset:2304
	global_atomic_add v4, v1, s[26:27] offset:2560
	global_atomic_add v4, v1, s[26:27] offset:2816
	global_atomic_add v4, v1, s[26:27] offset:3072
	global_atomic_add v4, v1, s[26:27] offset:3328
	global_atomic_add v4, v1, s[26:27] offset:3584
	global_atomic_add v4, v1, s[26:27] offset:3840
	s_waitcnt vmcnt(0)
	s_branch .Lxb8_done

.Lxb8_loop:
	global_load_dword v5, v4, s[26:27] sc1
	s_waitcnt vmcnt(0)
	v_cmp_ne_u32_e32 vcc, 8, v5
	s_cbranch_vccnz .Lxb8_done
	s_sleep 1
	s_add_u32 s99, s99, 1
	s_cmp_lt_u32 s99, 0x8000
	s_cbranch_scc1 .Lxb8_loop
.Lxb8_done:
	s_waitcnt vmcnt(0)
.LBB0_630:
	s_or_b64 exec, exec, s[4:5]
	s_waitcnt lgkmcnt(0)
	v_mov_b32_e32 v0, v205
	s_barrier
	s_mov_b32 s4, 0x8000
	v_ashrrev_i32_e32 v1, 6, v0
	v_add_u32_e32 v148, s93, v1
	v_cmp_gt_i32_e32 vcc, s4, v148
	s_and_saveexec_b64 s[6:7], vcc
	s_cbranch_execz .LBB0_637

.LBB0_637:
	s_or_b64 exec, exec, s[6:7]
	s_waitcnt vmcnt(0)
	v_mov_b32_e32 v0, v205
	s_barrier
	s_nop 0
	v_cmp_eq_u32_e32 vcc, 0, v0
	s_and_saveexec_b64 s[4:5], vcc
	s_cbranch_execz .LBB0_689
	buffer_inv sc1
	v_mov_b32_e32 v0, 0x12000
	ds_read_b64 v[2:3], v0
	s_getreg_b32 s98, hwreg(HW_REG_XCC_ID, 0, 4)
	s_and_b32 s98, s98, 15
	s_lshl_b32 s98, s98, 8
	v_mov_b32_e32 v1, 1
	s_add_u32 s100, s98, 0x1dc01400
	s_add_u32 s101, s98, 0x1dc02400
	v_mov_b32_e32 v4, s100
	s_waitcnt vmcnt(0) expcnt(0) lgkmcnt(0)
	global_atomic_add v5, v4, v1, s[26:27] sc0
	v_mul_lo_u32 v6, v2, 10
	s_waitcnt vmcnt(0)
	v_add_u32_e32 v5, 1, v5
	v_cmp_eq_u32_e32 vcc, v5, v6
	s_cbranch_vccz .Lxb9_spin
	buffer_wbl2 sc1
	s_waitcnt vmcnt(0)
	v_mov_b32_e32 v4, 0x1dc03400
	global_atomic_add v5, v4, v1, s[26:27] sc0
	v_mul_lo_u32 v6, v3, 10
	s_waitcnt vmcnt(0)
	v_add_u32_e32 v5, 1, v5
	v_cmp_eq_u32_e32 vcc, v5, v6
	s_cbranch_vccz .Lxb9_spin
	v_mov_b32_e32 v4, 0x1dc02400
	global_atomic_add v4, v1, s[26:27]
	global_atomic_add v4, v1, s[26:27] offset:256
	global_atomic_add v4, v1, s[26:27] offset:512
	global_atomic_add v4, v1, s[26:27] offset:768
	global_atomic_add v4, v1, s[26:27] offset:1024
	global_atomic_add v4, v1, s[26:27] offset:1280
	global_atomic_add v4, v1, s[26:27] offset:1536
	global_atomic_add v4, v1, s[26:27] offset:1792
	global_atomic_add v4, v1, s[26:27] offset:2048
	global_atomic_add v4, v1, s[26:27] offset:2304
	global_atomic_add v4, v1, s[26:27] offset:2560
	global_atomic_add v4, v1, s[26:27] offset:2816
	global_atomic_add v4, v1, s[26:27] offset:3072
	global_atomic_add v4, v1, s[26:27] offset:3328
	global_atomic_add v4, v1, s[26:27] offset:3584
	global_atomic_add v4, v1, s[26:27] offset:3840
	s_waitcnt vmcnt(0)
	s_branch .Lxb9_done

.Lxb9_loop:
	global_load_dword v5, v4, s[26:27] sc1
	s_waitcnt vmcnt(0)
	v_cmp_ne_u32_e32 vcc, 9, v5
	s_cbranch_vccnz .Lxb9_done
	s_sleep 1
	s_add_u32 s99, s99, 1
	s_cmp_lt_u32 s99, 0x8000
	s_cbranch_scc1 .Lxb9_loop
.Lxb9_done:
	s_waitcnt vmcnt(0)
.LBB0_689:
	s_or_b64 exec, exec, s[4:5]
	s_and_b64 vcc, exec, s[0:1]
	s_mov_b32 s16, s2
	s_waitcnt lgkmcnt(0)
	s_barrier
	s_cbranch_vccz .LBB0_691
	s_cmpk_gt_i32 s16, 0x9ff
	s_cbranch_scc0 .LBB0_692
	s_branch .LBB0_710

.LBB0_710:
	s_waitcnt vmcnt(0)
	v_mov_b32_e32 v0, v205
	s_barrier
	s_nop 0
	v_cmp_eq_u32_e32 vcc, 0, v0
	s_and_saveexec_b64 s[4:5], vcc
	s_cbranch_execz .LBB0_762
	buffer_inv sc1
	v_mov_b32_e32 v0, 0x12000
	ds_read_b64 v[2:3], v0
	s_getreg_b32 s98, hwreg(HW_REG_XCC_ID, 0, 4)
	s_and_b32 s98, s98, 15
	s_lshl_b32 s98, s98, 8
	v_mov_b32_e32 v1, 1
	s_add_u32 s100, s98, 0x1dc01400
	s_add_u32 s101, s98, 0x1dc02400
	v_mov_b32_e32 v4, s100
	s_waitcnt vmcnt(0) expcnt(0) lgkmcnt(0)
	global_atomic_add v5, v4, v1, s[26:27] sc0
	v_mul_lo_u32 v6, v2, 11
	s_waitcnt vmcnt(0)
	v_add_u32_e32 v5, 1, v5
	v_cmp_eq_u32_e32 vcc, v5, v6
	s_cbranch_vccz .Lxb10_spin
	buffer_wbl2 sc1
	s_waitcnt vmcnt(0)
	v_mov_b32_e32 v4, 0x1dc03400
	global_atomic_add v5, v4, v1, s[26:27] sc0
	v_mul_lo_u32 v6, v3, 11
	s_waitcnt vmcnt(0)
	v_add_u32_e32 v5, 1, v5
	v_cmp_eq_u32_e32 vcc, v5, v6
	s_cbranch_vccz .Lxb10_spin
	v_mov_b32_e32 v4, 0x1dc02400
	global_atomic_add v4, v1, s[26:27]
	global_atomic_add v4, v1, s[26:27] offset:256
	global_atomic_add v4, v1, s[26:27] offset:512
	global_atomic_add v4, v1, s[26:27] offset:768
	global_atomic_add v4, v1, s[26:27] offset:1024
	global_atomic_add v4, v1, s[26:27] offset:1280
	global_atomic_add v4, v1, s[26:27] offset:1536
	global_atomic_add v4, v1, s[26:27] offset:1792
	global_atomic_add v4, v1, s[26:27] offset:2048
	global_atomic_add v4, v1, s[26:27] offset:2304
	global_atomic_add v4, v1, s[26:27] offset:2560
	global_atomic_add v4, v1, s[26:27] offset:2816
	global_atomic_add v4, v1, s[26:27] offset:3072
	global_atomic_add v4, v1, s[26:27] offset:3328
	global_atomic_add v4, v1, s[26:27] offset:3584
	global_atomic_add v4, v1, s[26:27] offset:3840
	s_waitcnt vmcnt(0)
	s_branch .Lxb10_done

.Lxb10_loop:
	global_load_dword v5, v4, s[26:27] sc1
	s_waitcnt vmcnt(0)
	v_cmp_ne_u32_e32 vcc, 10, v5
	s_cbranch_vccnz .Lxb10_done
	s_sleep 1
	s_add_u32 s99, s99, 1
	s_cmp_lt_u32 s99, 0x8000
	s_cbranch_scc1 .Lxb10_loop
.Lxb10_done:
	s_waitcnt vmcnt(0)
.LBB0_762:
	s_or_b64 exec, exec, s[4:5]
	s_cmpk_gt_i32 s2, 0x1ff
	s_waitcnt lgkmcnt(0)
	s_barrier
	s_cbranch_scc1 .LBB0_781
	s_waitcnt vmcnt(4)
	v_mbcnt_hi_u32_b32 v89, -1, v207
	v_and_b32_e32 v0, 64, v89
	s_lshl_b32 s38, s2, 6
	s_add_i32 s39, s92, -1
	s_lshl_b32 s39, s39, 3
	s_mov_b32 s17, 0
	v_mov_b32_e32 v81, 0
	s_movk_i32 s40, 0xa00
	s_movk_i32 s41, 0x1070
	s_movk_i32 s50, 0x90
	v_mov_b64_e32 v[82:83], s[44:45]
	s_movk_i32 s51, 0x7f
	v_mov_b32_e32 v88, 0xff800000
	s_movk_i32 s52, 0x7e
	v_xor_b32_e32 v90, 32, v89
	v_add_u32_e32 v91, 64, v0
	s_lshl_b32 s53, s2, 3
	s_branch .LBB0_765

.LBB0_781:
	s_waitcnt vmcnt(0)
	v_mov_b32_e32 v0, v205
	s_barrier
	s_nop 0
	v_cmp_eq_u32_e32 vcc, 0, v0
	s_and_saveexec_b64 s[4:5], vcc
	s_cbranch_execz .LBB0_833
	buffer_inv sc1
	v_mov_b32_e32 v0, 0x12000
	ds_read_b64 v[2:3], v0
	s_getreg_b32 s98, hwreg(HW_REG_XCC_ID, 0, 4)
	s_and_b32 s98, s98, 15
	s_lshl_b32 s98, s98, 8
	v_mov_b32_e32 v1, 1
	s_add_u32 s100, s98, 0x1dc01400
	s_add_u32 s101, s98, 0x1dc02400
	v_mov_b32_e32 v4, s100
	s_waitcnt vmcnt(0) expcnt(0) lgkmcnt(0)
	global_atomic_add v5, v4, v1, s[26:27] sc0
	v_mul_lo_u32 v6, v2, 12
	s_waitcnt vmcnt(0)
	v_add_u32_e32 v5, 1, v5
	v_cmp_eq_u32_e32 vcc, v5, v6
	s_cbranch_vccz .Lxb11_spin
	buffer_wbl2 sc1
	s_waitcnt vmcnt(0)
	v_mov_b32_e32 v4, 0x1dc03400
	global_atomic_add v5, v4, v1, s[26:27] sc0
	v_mul_lo_u32 v6, v3, 12
	s_waitcnt vmcnt(0)
	v_add_u32_e32 v5, 1, v5
	v_cmp_eq_u32_e32 vcc, v5, v6
	s_cbranch_vccz .Lxb11_spin
	v_mov_b32_e32 v4, 0x1dc02400
	global_atomic_add v4, v1, s[26:27]
	global_atomic_add v4, v1, s[26:27] offset:256
	global_atomic_add v4, v1, s[26:27] offset:512
	global_atomic_add v4, v1, s[26:27] offset:768
	global_atomic_add v4, v1, s[26:27] offset:1024
	global_atomic_add v4, v1, s[26:27] offset:1280
	global_atomic_add v4, v1, s[26:27] offset:1536
	global_atomic_add v4, v1, s[26:27] offset:1792
	global_atomic_add v4, v1, s[26:27] offset:2048
	global_atomic_add v4, v1, s[26:27] offset:2304
	global_atomic_add v4, v1, s[26:27] offset:2560
	global_atomic_add v4, v1, s[26:27] offset:2816
	global_atomic_add v4, v1, s[26:27] offset:3072
	global_atomic_add v4, v1, s[26:27] offset:3328
	global_atomic_add v4, v1, s[26:27] offset:3584
	global_atomic_add v4, v1, s[26:27] offset:3840
	s_waitcnt vmcnt(0)
	s_branch .Lxb11_done

.Lxb11_loop:
	global_load_dword v5, v4, s[26:27] sc1
	s_waitcnt vmcnt(0)
	v_cmp_ne_u32_e32 vcc, 11, v5
	s_cbranch_vccnz .Lxb11_done
	s_sleep 1
	s_add_u32 s99, s99, 1
	s_cmp_lt_u32 s99, 0x8000
	s_cbranch_scc1 .Lxb11_loop
.Lxb11_done:
	s_waitcnt vmcnt(0)
.LBB0_833:
	s_or_b64 exec, exec, s[4:5]
	s_and_b64 vcc, exec, s[0:1]
	s_mov_b32 s10, s2
	s_waitcnt lgkmcnt(0)
	s_barrier
	s_cbranch_vccz .LBB0_835
	s_cmpk_gt_i32 s10, 0x7ff
	s_cbranch_scc0 .LBB0_836
	s_branch .LBB0_848

.LBB0_848:
	s_waitcnt vmcnt(0)
	v_mov_b32_e32 v0, v205
	s_barrier
	s_nop 0
	v_cmp_eq_u32_e32 vcc, 0, v0
	s_and_saveexec_b64 s[4:5], vcc
	s_cbranch_execz .LBB0_900
	buffer_inv sc1
	v_mov_b32_e32 v0, 0x12000
	ds_read_b64 v[2:3], v0
	s_getreg_b32 s98, hwreg(HW_REG_XCC_ID, 0, 4)
	s_and_b32 s98, s98, 15
	s_lshl_b32 s98, s98, 8
	v_mov_b32_e32 v1, 1
	s_add_u32 s100, s98, 0x1dc01400
	s_add_u32 s101, s98, 0x1dc02400
	v_mov_b32_e32 v4, s100
	s_waitcnt vmcnt(0) expcnt(0) lgkmcnt(0)
	global_atomic_add v5, v4, v1, s[26:27] sc0
	v_mul_lo_u32 v6, v2, 13
	s_waitcnt vmcnt(0)
	v_add_u32_e32 v5, 1, v5
	v_cmp_eq_u32_e32 vcc, v5, v6
	s_cbranch_vccz .Lxb12_spin
	buffer_wbl2 sc1
	s_waitcnt vmcnt(0)
	v_mov_b32_e32 v4, 0x1dc03400
	global_atomic_add v5, v4, v1, s[26:27] sc0
	v_mul_lo_u32 v6, v3, 13
	s_waitcnt vmcnt(0)
	v_add_u32_e32 v5, 1, v5
	v_cmp_eq_u32_e32 vcc, v5, v6
	s_cbranch_vccz .Lxb12_spin
	v_mov_b32_e32 v4, 0x1dc02400
	global_atomic_add v4, v1, s[26:27]
	global_atomic_add v4, v1, s[26:27] offset:256
	global_atomic_add v4, v1, s[26:27] offset:512
	global_atomic_add v4, v1, s[26:27] offset:768
	global_atomic_add v4, v1, s[26:27] offset:1024
	global_atomic_add v4, v1, s[26:27] offset:1280
	global_atomic_add v4, v1, s[26:27] offset:1536
	global_atomic_add v4, v1, s[26:27] offset:1792
	global_atomic_add v4, v1, s[26:27] offset:2048
	global_atomic_add v4, v1, s[26:27] offset:2304
	global_atomic_add v4, v1, s[26:27] offset:2560
	global_atomic_add v4, v1, s[26:27] offset:2816
	global_atomic_add v4, v1, s[26:27] offset:3072
	global_atomic_add v4, v1, s[26:27] offset:3328
	global_atomic_add v4, v1, s[26:27] offset:3584
	global_atomic_add v4, v1, s[26:27] offset:3840
	s_waitcnt vmcnt(0)
	s_branch .Lxb12_done

.Lxb12_loop:
	global_load_dword v5, v4, s[26:27] sc1
	s_waitcnt vmcnt(0)
	v_cmp_ne_u32_e32 vcc, 12, v5
	s_cbranch_vccnz .Lxb12_done
	s_sleep 1
	s_add_u32 s99, s99, 1
	s_cmp_lt_u32 s99, 0x8000
	s_cbranch_scc1 .Lxb12_loop
.Lxb12_done:
	s_waitcnt vmcnt(0)
.LBB0_900:
	s_or_b64 exec, exec, s[4:5]
	s_waitcnt lgkmcnt(0)
	v_mov_b32_e32 v0, v205
	v_mov_b32_e32 v1, v205
	s_barrier
	s_mov_b32 s4, 0x8000
	v_ashrrev_i32_e32 v1, 6, v1
	v_add_u32_e32 v16, s93, v1
	v_cmp_gt_i32_e32 vcc, s4, v16
	s_and_saveexec_b64 s[6:7], vcc
	s_cbranch_execz .LBB0_903
	v_and_b32_e32 v17, 63, v0
	s_add_u32 s4, s42, 0x1000
	v_or_b32_e32 v20, 64, v17
	v_or_b32_e32 v21, 0x80, v17
	s_addc_u32 s5, s43, 0
	v_lshlrev_b32_e32 v18, 4, v17
	v_or_b32_e32 v23, 0xc0, v17
	v_lshlrev_b32_e32 v8, 4, v20
	v_lshlrev_b32_e32 v9, 4, v21
	global_load_dwordx4 v[0:3], v8, s[4:5]
	global_load_dwordx4 v[4:7], v9, s[4:5]
	v_lshlrev_b32_e32 v19, 4, v23
	global_load_dwordx4 v[8:11], v18, s[4:5]
	global_load_dwordx4 v[12:15], v19, s[4:5]
	v_mbcnt_hi_u32_b32 v22, -1, v207
	v_and_b32_e32 v19, 64, v22
	v_add_u32_e32 v24, 64, v19
	v_xor_b32_e32 v25, 32, v22
	v_cmp_lt_i32_e32 vcc, v25, v24
	v_mov_b32_e32 v19, 0
	v_lshlrev_b32_e32 v26, 2, v21
	v_cndmask_b32_e32 v25, v22, v25, vcc
	v_lshlrev_b32_e32 v28, 2, v25
	v_xor_b32_e32 v25, 16, v22
	v_cmp_lt_i32_e32 vcc, v25, v24
	v_lshlrev_b32_e32 v36, 2, v23
	s_lshl_b32 s10, s92, 2
	v_cndmask_b32_e32 v25, v22, v25, vcc
	v_lshlrev_b32_e32 v29, 2, v25
	v_xor_b32_e32 v25, 8, v22
	v_cmp_lt_i32_e32 vcc, v25, v24
	s_mov_b64 s[8:9], 0
	v_mov_b32_e32 v23, v19
	v_cndmask_b32_e32 v25, v22, v25, vcc
	v_lshlrev_b32_e32 v30, 2, v25
	v_xor_b32_e32 v25, 4, v22
	v_cmp_lt_i32_e32 vcc, v25, v24
	v_mov_b32_e32 v34, 0x358637bd
	s_mov_b32 s11, 0x800000
	v_cndmask_b32_e32 v25, v22, v25, vcc
	v_lshlrev_b32_e32 v31, 2, v25
	v_xor_b32_e32 v25, 2, v22
	v_cmp_lt_i32_e32 vcc, v25, v24
	v_mov_b32_e32 v27, v19
	s_movk_i32 s12, 0x7fff
	v_cndmask_b32_e32 v25, v22, v25, vcc
	v_lshlrev_b32_e32 v32, 2, v25
	v_xor_b32_e32 v25, 1, v22
	v_cmp_lt_i32_e32 vcc, v25, v24
	v_lshlrev_b32_e32 v24, 2, v20
	v_lshl_add_u64 v[20:21], s[24:25], 0, v[18:19]
	v_cndmask_b32_e32 v22, v22, v25, vcc
	v_lshlrev_b32_e32 v33, 2, v22
	v_lshlrev_b32_e32 v22, 2, v17
	v_lshlrev_b32_e32 v18, 1, v22
	v_lshlrev_b32_e32 v22, 1, v24
	v_lshlrev_b32_e32 v24, 1, v26
	v_mov_b32_e32 v25, v19
	v_lshlrev_b32_e32 v26, 1, v36

.LBB0_903:
	s_or_b64 exec, exec, s[6:7]
	s_waitcnt vmcnt(0)
	v_mov_b32_e32 v0, v205
	s_barrier
	s_nop 0
	v_cmp_eq_u32_e32 vcc, 0, v0
	s_and_saveexec_b64 s[4:5], vcc
	s_cbranch_execz .LBB0_955
	buffer_inv sc1
	v_mov_b32_e32 v0, 0x12000
	ds_read_b64 v[2:3], v0
	s_getreg_b32 s98, hwreg(HW_REG_XCC_ID, 0, 4)
	s_and_b32 s98, s98, 15
	s_lshl_b32 s98, s98, 8
	v_mov_b32_e32 v1, 1
	s_add_u32 s100, s98, 0x1dc01400
	s_add_u32 s101, s98, 0x1dc02400
	v_mov_b32_e32 v4, s100
	s_waitcnt vmcnt(0) expcnt(0) lgkmcnt(0)
	global_atomic_add v5, v4, v1, s[26:27] sc0
	v_mul_lo_u32 v6, v2, 14
	s_waitcnt vmcnt(0)
	v_add_u32_e32 v5, 1, v5
	v_cmp_eq_u32_e32 vcc, v5, v6
	s_cbranch_vccz .Lxb13_spin
	buffer_wbl2 sc1
	s_waitcnt vmcnt(0)
	v_mov_b32_e32 v4, 0x1dc03400
	global_atomic_add v5, v4, v1, s[26:27] sc0
	v_mul_lo_u32 v6, v3, 14
	s_waitcnt vmcnt(0)
	v_add_u32_e32 v5, 1, v5
	v_cmp_eq_u32_e32 vcc, v5, v6
	s_cbranch_vccz .Lxb13_spin
	v_mov_b32_e32 v4, 0x1dc02400
	global_atomic_add v4, v1, s[26:27]
	global_atomic_add v4, v1, s[26:27] offset:256
	global_atomic_add v4, v1, s[26:27] offset:512
	global_atomic_add v4, v1, s[26:27] offset:768
	global_atomic_add v4, v1, s[26:27] offset:1024
	global_atomic_add v4, v1, s[26:27] offset:1280
	global_atomic_add v4, v1, s[26:27] offset:1536
	global_atomic_add v4, v1, s[26:27] offset:1792
	global_atomic_add v4, v1, s[26:27] offset:2048
	global_atomic_add v4, v1, s[26:27] offset:2304
	global_atomic_add v4, v1, s[26:27] offset:2560
	global_atomic_add v4, v1, s[26:27] offset:2816
	global_atomic_add v4, v1, s[26:27] offset:3072
	global_atomic_add v4, v1, s[26:27] offset:3328
	global_atomic_add v4, v1, s[26:27] offset:3584
	global_atomic_add v4, v1, s[26:27] offset:3840
	s_waitcnt vmcnt(0)
	s_branch .Lxb13_done

.Lxb13_loop:
	global_load_dword v5, v4, s[26:27] sc1
	s_waitcnt vmcnt(0)
	v_cmp_ne_u32_e32 vcc, 13, v5
	s_cbranch_vccnz .Lxb13_done
	s_sleep 1
	s_add_u32 s99, s99, 1
	s_cmp_lt_u32 s99, 0x8000
	s_cbranch_scc1 .Lxb13_loop
.Lxb13_done:
	s_waitcnt vmcnt(0)
.LBB0_955:
	s_or_b64 exec, exec, s[4:5]
	s_and_b64 vcc, exec, s[0:1]
	s_waitcnt lgkmcnt(0)
	s_barrier
	s_cbranch_vccz .LBB0_957
	s_cmpk_gt_i32 s2, 0x7ff
	s_cbranch_scc0 .LBB0_958
	s_branch .LBB0_970

.LBB0_970:
	s_waitcnt vmcnt(0)
	v_mov_b32_e32 v0, v205
	s_barrier
	s_nop 0
	v_cmp_eq_u32_e32 vcc, 0, v0
	s_and_saveexec_b64 s[0:1], vcc
	s_cbranch_execz .LBB0_1022
	buffer_inv sc1
	v_mov_b32_e32 v0, 0x12000
	ds_read_b64 v[2:3], v0
	s_getreg_b32 s98, hwreg(HW_REG_XCC_ID, 0, 4)
	s_and_b32 s98, s98, 15
	s_lshl_b32 s98, s98, 8
	v_mov_b32_e32 v1, 1
	s_add_u32 s100, s98, 0x1dc01400
	s_add_u32 s101, s98, 0x1dc02400
	v_mov_b32_e32 v4, s100
	s_waitcnt vmcnt(0) expcnt(0) lgkmcnt(0)
	global_atomic_add v5, v4, v1, s[26:27] sc0
	v_mul_lo_u32 v6, v2, 15
	s_waitcnt vmcnt(0)
	v_add_u32_e32 v5, 1, v5
	v_cmp_eq_u32_e32 vcc, v5, v6
	s_cbranch_vccz .Lxb14_spin
	buffer_wbl2 sc1
	s_waitcnt vmcnt(0)
	v_mov_b32_e32 v4, 0x1dc03400
	global_atomic_add v5, v4, v1, s[26:27] sc0
	v_mul_lo_u32 v6, v3, 15
	s_waitcnt vmcnt(0)
	v_add_u32_e32 v5, 1, v5
	v_cmp_eq_u32_e32 vcc, v5, v6
	s_cbranch_vccz .Lxb14_spin
	v_mov_b32_e32 v4, 0x1dc02400
	global_atomic_add v4, v1, s[26:27]
	global_atomic_add v4, v1, s[26:27] offset:256
	global_atomic_add v4, v1, s[26:27] offset:512
	global_atomic_add v4, v1, s[26:27] offset:768
	global_atomic_add v4, v1, s[26:27] offset:1024
	global_atomic_add v4, v1, s[26:27] offset:1280
	global_atomic_add v4, v1, s[26:27] offset:1536
	global_atomic_add v4, v1, s[26:27] offset:1792
	global_atomic_add v4, v1, s[26:27] offset:2048
	global_atomic_add v4, v1, s[26:27] offset:2304
	global_atomic_add v4, v1, s[26:27] offset:2560
	global_atomic_add v4, v1, s[26:27] offset:2816
	global_atomic_add v4, v1, s[26:27] offset:3072
	global_atomic_add v4, v1, s[26:27] offset:3328
	global_atomic_add v4, v1, s[26:27] offset:3584
	global_atomic_add v4, v1, s[26:27] offset:3840
	s_waitcnt vmcnt(0)
	s_branch .Lxb14_done

.Lxb14_loop:
	global_load_dword v5, v4, s[26:27] sc1
	s_waitcnt vmcnt(0)
	v_cmp_ne_u32_e32 vcc, 14, v5
	s_cbranch_vccnz .Lxb14_done
	s_sleep 1
	s_add_u32 s99, s99, 1
	s_cmp_lt_u32 s99, 0x8000
	s_cbranch_scc1 .Lxb14_loop
.Lxb14_done:
	s_waitcnt vmcnt(0)
.LBB0_1022:
	s_or_b64 exec, exec, s[0:1]
	s_waitcnt lgkmcnt(0)
	v_mov_b32_e32 v0, v205
	s_barrier
	s_mov_b32 s0, 0x8000
	v_ashrrev_i32_e32 v1, 6, v0
	v_add_u32_e32 v176, s93, v1
	v_cmp_gt_i32_e32 vcc, s0, v176
	s_and_saveexec_b64 s[2:3], vcc
	s_cbranch_execz .LBB0_1045

.LBB0_1045:
	s_or_b64 exec, exec, s[2:3]
	s_waitcnt vmcnt(0)
	v_mov_b32_e32 v0, v205
	s_barrier
	s_nop 0
	v_cmp_eq_u32_e32 vcc, 0, v0
	s_and_saveexec_b64 s[0:1], vcc
	s_cbranch_execz .LBB0_1097
	buffer_inv sc1
	v_mov_b32_e32 v0, 0x12000
	ds_read_b64 v[2:3], v0
	s_getreg_b32 s98, hwreg(HW_REG_XCC_ID, 0, 4)
	s_and_b32 s98, s98, 15
	s_lshl_b32 s98, s98, 8
	v_mov_b32_e32 v1, 1
	s_add_u32 s100, s98, 0x1dc01400
	s_add_u32 s101, s98, 0x1dc02400
	v_mov_b32_e32 v4, s100
	s_waitcnt vmcnt(0) expcnt(0) lgkmcnt(0)
	global_atomic_add v5, v4, v1, s[26:27] sc0
	v_mul_lo_u32 v6, v2, 16
	s_waitcnt vmcnt(0)
	v_add_u32_e32 v5, 1, v5
	v_cmp_eq_u32_e32 vcc, v5, v6
	s_cbranch_vccz .Lxb15_spin
	buffer_wbl2 sc1
	s_waitcnt vmcnt(0)
	v_mov_b32_e32 v4, 0x1dc03400
	global_atomic_add v5, v4, v1, s[26:27] sc0
	v_mul_lo_u32 v6, v3, 16
	s_waitcnt vmcnt(0)
	v_add_u32_e32 v5, 1, v5
	v_cmp_eq_u32_e32 vcc, v5, v6
	s_cbranch_vccz .Lxb15_spin
	v_mov_b32_e32 v4, 0x1dc02400
	global_atomic_add v4, v1, s[26:27]
	global_atomic_add v4, v1, s[26:27] offset:256
	global_atomic_add v4, v1, s[26:27] offset:512
	global_atomic_add v4, v1, s[26:27] offset:768
	global_atomic_add v4, v1, s[26:27] offset:1024
	global_atomic_add v4, v1, s[26:27] offset:1280
	global_atomic_add v4, v1, s[26:27] offset:1536
	global_atomic_add v4, v1, s[26:27] offset:1792
	global_atomic_add v4, v1, s[26:27] offset:2048
	global_atomic_add v4, v1, s[26:27] offset:2304
	global_atomic_add v4, v1, s[26:27] offset:2560
	global_atomic_add v4, v1, s[26:27] offset:2816
	global_atomic_add v4, v1, s[26:27] offset:3072
	global_atomic_add v4, v1, s[26:27] offset:3328
	global_atomic_add v4, v1, s[26:27] offset:3584
	global_atomic_add v4, v1, s[26:27] offset:3840
	s_waitcnt vmcnt(0)
	s_branch .Lxb15_done

.Lxb15_loop:
	global_load_dword v5, v4, s[26:27] sc1
	s_waitcnt vmcnt(0)
	v_cmp_ne_u32_e32 vcc, 15, v5
	s_cbranch_vccnz .Lxb15_done
	s_sleep 1
	s_add_u32 s99, s99, 1
	s_cmp_lt_u32 s99, 0x8000
	s_cbranch_scc1 .Lxb15_loop
.Lxb15_done:
	s_waitcnt vmcnt(0)
.LBB0_1097:
	s_or_b64 exec, exec, s[0:1]
	s_waitcnt lgkmcnt(0)
	s_barrier
	s_mov_b32 s0, 0x8000
	v_ashrrev_i32_e32 v0, 6, v205
	v_add_u32_e32 v148, s93, v0
	v_cmp_gt_i32_e32 vcc, s0, v148
	s_and_saveexec_b64 s[0:1], vcc
	s_cbranch_execz .LBB0_1104
